# v47 + GEMM4 epilogue conv/silu core rewritten by hand in packed-f32 form (single select per neighbour, pk_fma conv, pk_mul silu), same math
# speedup vs baseline: 1.0105x; 1.0094x over previous
; #define PG8_LAS __attribute__((address_space(3)))
;     __device__ __forceinline__ void run(const f32x4 (&acc)[2][2][4][2], const Unit& u, int wr, int wc, int fr, int fq, PG8_LAS unsigned char* lds, int buf) const {
;     ...
;         f32x4 w0[2], w1[2], w2[2], bb[2];
; #pragma unroll
;         for (int n = 0; n < 2; ++n) { w0[n] = *(const PG8_LAS f32x4*)(vl + 4 * n); w1[n] = *(const PG8_LAS f32x4*)(vl + 128 + 4 * n); w2[n] = *(const PG8_LAS f32x4*)(vl + 256 + 4 * n); bb[n] = *(const PG8_LAS f32x4*)(vl + 384 + 4 * n); }
; #pragma unroll
;         for (int ai = 0; ai < 2; ++ai) {
;             unsigned op[4][2][2];
; #pragma unroll
;             for (int n = 0; n < 2; ++n)
; #pragma unroll
;                 for (int ep = 0; ep < 2; ++ep) {
;                     float ov[4][2], xv[4][2];
; #pragma unroll
;                     for (int eh = 0; eh < 2; ++eh) { const int e = 2 * ep + eh;
;                         float R[4], L[4];
; #pragma unroll
;                         for (int m = 0; m < 4; ++m) { R[m] = dpp_ror<1>(acc[ai][1][m][n][e]); L[m] = dpp_ror<15>(acc[ai][1][m][n][e]); }
; #pragma unroll
;                         for (int m = 0; m < 4; ++m) {
;                             const float up = (fr == 0) ? R[m > 0 ? m - 1 : 0] : R[m];
;                             const float dn = (fr == 15) ? L[m < 3 ? m + 1 : 3] : L[m];
;                             xv[m][eh] = up * w0[n][e] + acc[ai][1][m][n][e] * w1[n][e] + dn * w2[n][e] + bb[n][e];
;                         } }
; #pragma unroll
;                     for (int m = 0; m < 4; ++m) {
;                         const float p0 = __builtin_amdgcn_exp2f(fminf(-1.4426950408889634f * xv[m][0], 60.0f)) + 1.0f, p1 = __builtin_amdgcn_exp2f(fminf(-1.4426950408889634f * xv[m][1], 60.0f)) + 1.0f;
;                         const float r = __builtin_amdgcn_rcpf(p0 * p1);
;                         const bool edge = (m == 0 && fr == 0) || (m == 3 && fr == 15);
;                         ov[m][0] = edge ? acc[ai][0][m][n][2 * ep] : xv[m][0] * (r * p1) * acc[ai][0][m][n][2 * ep];
;                         ov[m][1] = edge ? acc[ai][0][m][n][2 * ep + 1] : xv[m][1] * (r * p0) * acc[ai][0][m][n][2 * ep + 1];
;                     }
; #pragma unroll
;                     for (int m = 0; m < 4; ++m) op[m][n][ep] = cvt_pk_bf16(ov[m][0], ov[m][1]);
.LBB0_1162:
	s_lshl_b32 s23, s23, 11
	s_and_b32 s23, s23, 0x800
	v_add_u32_e32 v70, s23, v179
	ds_read_b128 v[122:125], v70
	ds_read_b128 v[66:69], v70 offset:16
	ds_read_b128 v[126:129], v70 offset:512
	ds_read_b128 v[74:77], v70 offset:528
	ds_read_b128 v[134:137], v70 offset:1024
	ds_read_b128 v[78:81], v70 offset:1040
	ds_read_b128 v[130:133], v70 offset:1536
	ds_read_b128 v[70:73], v70 offset:1552
	v_lshl_add_u32 v194, s56, 8, v175
	v_lshl_or_b32 v188, s57, 7, v192
	s_lshl_b32 s23, s56, 2
	v_ashrrev_i32_e32 v189, 31, v188
	s_add_i32 s23, s23, s83
	v_cmp_eq_u32_e64 s[48:49], 0, v21
	v_cmp_eq_u32_e64 s[50:51], 15, v21
	s_mov_b32 s52, 0xbfb8aa3b
	s_mov_b32 s53, 0xbfb8aa3b
	v_mov_b32_dpp v196, v94 row_ror:1 row_mask:0xf bank_mask:0xf
	v_mov_b32_dpp v197, v95 row_ror:1 row_mask:0xf bank_mask:0xf
	v_mov_b32_dpp v198, v158 row_ror:1 row_mask:0xf bank_mask:0xf
	v_mov_b32_dpp v199, v159 row_ror:1 row_mask:0xf bank_mask:0xf
	v_mov_b32_dpp v200, v154 row_ror:1 row_mask:0xf bank_mask:0xf
	v_mov_b32_dpp v201, v155 row_ror:1 row_mask:0xf bank_mask:0xf
	v_mov_b32_dpp v202, v86 row_ror:1 row_mask:0xf bank_mask:0xf
	v_mov_b32_dpp v203, v87 row_ror:1 row_mask:0xf bank_mask:0xf
	v_mov_b32_dpp v204, v94 row_ror:15 row_mask:0xf bank_mask:0xf
	v_mov_b32_dpp v205, v95 row_ror:15 row_mask:0xf bank_mask:0xf
	v_mov_b32_dpp v208, v158 row_ror:15 row_mask:0xf bank_mask:0xf
	v_mov_b32_dpp v209, v159 row_ror:15 row_mask:0xf bank_mask:0xf
	v_mov_b32_dpp v210, v154 row_ror:15 row_mask:0xf bank_mask:0xf
	v_mov_b32_dpp v211, v155 row_ror:15 row_mask:0xf bank_mask:0xf
	v_mov_b32_dpp v214, v86 row_ror:15 row_mask:0xf bank_mask:0xf
	v_mov_b32_dpp v215, v87 row_ror:15 row_mask:0xf bank_mask:0xf
	s_waitcnt lgkmcnt(0)
	v_cndmask_b32_e64 v202, v202, v200, s[48:49]
	v_cndmask_b32_e64 v203, v203, v201, s[48:49]
	v_cndmask_b32_e64 v200, v200, v198, s[48:49]
	v_cndmask_b32_e64 v201, v201, v199, s[48:49]
	v_cndmask_b32_e64 v198, v198, v196, s[48:49]
	v_cndmask_b32_e64 v199, v199, v197, s[48:49]
	v_cndmask_b32_e64 v204, v204, v208, s[50:51]
	v_cndmask_b32_e64 v205, v205, v209, s[50:51]
	v_cndmask_b32_e64 v208, v208, v210, s[50:51]
	v_cndmask_b32_e64 v209, v209, v211, s[50:51]
	v_cndmask_b32_e64 v210, v210, v214, s[50:51]
	v_cndmask_b32_e64 v211, v211, v215, s[50:51]
	v_pk_fma_f32 v[204:205], v[204:205], v[134:135], v[130:131]
	v_pk_fma_f32 v[208:209], v[208:209], v[134:135], v[130:131]
	v_pk_fma_f32 v[210:211], v[210:211], v[134:135], v[130:131]
	v_pk_fma_f32 v[214:215], v[214:215], v[134:135], v[130:131]
	v_pk_fma_f32 v[204:205], v[94:95], v[126:127], v[204:205]
	v_pk_fma_f32 v[208:209], v[158:159], v[126:127], v[208:209]
	v_pk_fma_f32 v[210:211], v[154:155], v[126:127], v[210:211]
	v_pk_fma_f32 v[214:215], v[86:87], v[126:127], v[214:215]
	v_pk_fma_f32 v[204:205], v[196:197], v[122:123], v[204:205]
	v_pk_fma_f32 v[208:209], v[198:199], v[122:123], v[208:209]
	v_pk_fma_f32 v[210:211], v[200:201], v[122:123], v[210:211]
	v_pk_fma_f32 v[214:215], v[202:203], v[122:123], v[214:215]
	v_pk_mul_f32 v[196:197], v[204:205], s[52:53]
	v_pk_mul_f32 v[198:199], v[208:209], s[52:53]
	v_pk_mul_f32 v[200:201], v[210:211], s[52:53]
	v_pk_mul_f32 v[202:203], v[214:215], s[52:53]
	v_min_f32_e32 v196, 0x42700000, v196
	v_min_f32_e32 v197, 0x42700000, v197
	v_min_f32_e32 v198, 0x42700000, v198
	v_min_f32_e32 v199, 0x42700000, v199
	v_min_f32_e32 v200, 0x42700000, v200
	v_min_f32_e32 v201, 0x42700000, v201
	v_min_f32_e32 v202, 0x42700000, v202
	v_min_f32_e32 v203, 0x42700000, v203
	v_exp_f32_e32 v196, v196
	v_exp_f32_e32 v197, v197
	v_exp_f32_e32 v198, v198
	v_exp_f32_e32 v199, v199
	v_exp_f32_e32 v200, v200
	v_exp_f32_e32 v201, v201
	v_exp_f32_e32 v202, v202
	v_exp_f32_e32 v203, v203
	v_pk_add_f32 v[196:197], v[196:197], 1.0 op_sel_hi:[1,0]
	v_pk_add_f32 v[198:199], v[198:199], 1.0 op_sel_hi:[1,0]
	v_pk_add_f32 v[200:201], v[200:201], 1.0 op_sel_hi:[1,0]
	v_pk_add_f32 v[202:203], v[202:203], 1.0 op_sel_hi:[1,0]
	v_mul_f32_e32 v216, v196, v197
	v_mul_f32_e32 v217, v198, v199
	v_mul_f32_e32 v218, v200, v201
	v_mul_f32_e32 v219, v202, v203
	v_rcp_f32_e32 v216, v216
	v_rcp_f32_e32 v217, v217
	v_rcp_f32_e32 v218, v218
	v_rcp_f32_e32 v219, v219
	v_pk_mul_f32 v[196:197], v[196:197], v[216:217] op_sel:[1,0] op_sel_hi:[0,0]
	v_pk_mul_f32 v[198:199], v[198:199], v[216:217] op_sel:[1,1] op_sel_hi:[0,1]
	v_pk_mul_f32 v[200:201], v[200:201], v[218:219] op_sel:[1,0] op_sel_hi:[0,0]
	v_pk_mul_f32 v[202:203], v[202:203], v[218:219] op_sel:[1,1] op_sel_hi:[0,1]
	v_pk_mul_f32 v[204:205], v[204:205], v[196:197]
	v_pk_mul_f32 v[208:209], v[208:209], v[198:199]
	v_pk_mul_f32 v[210:211], v[210:211], v[200:201]
	v_pk_mul_f32 v[214:215], v[214:215], v[202:203]
	v_pk_mul_f32 v[204:205], v[204:205], v[150:151]
	v_pk_mul_f32 v[208:209], v[208:209], v[146:147]
	v_pk_mul_f32 v[210:211], v[210:211], v[142:143]
	v_pk_mul_f32 v[214:215], v[214:215], v[138:139]
	v_cndmask_b32_e64 v204, v204, v150, s[48:49]
	v_cndmask_b32_e64 v205, v205, v151, s[48:49]
	v_cndmask_b32_e64 v214, v214, v138, s[50:51]
	v_cndmask_b32_e64 v215, v215, v139, s[50:51]
	v_cvt_pk_bf16_f32 v150, v204, v205
	v_cvt_pk_bf16_f32 v146, v208, v209
	v_cvt_pk_bf16_f32 v142, v210, v211
	v_cvt_pk_bf16_f32 v138, v214, v215
	v_mov_b32_dpp v196, v96 row_ror:1 row_mask:0xf bank_mask:0xf
	v_mov_b32_dpp v197, v97 row_ror:1 row_mask:0xf bank_mask:0xf
	v_mov_b32_dpp v198, v160 row_ror:1 row_mask:0xf bank_mask:0xf
	v_mov_b32_dpp v199, v161 row_ror:1 row_mask:0xf bank_mask:0xf
	v_mov_b32_dpp v200, v156 row_ror:1 row_mask:0xf bank_mask:0xf
	v_mov_b32_dpp v201, v157 row_ror:1 row_mask:0xf bank_mask:0xf
	v_mov_b32_dpp v202, v88 row_ror:1 row_mask:0xf bank_mask:0xf
; template <int N> __device__ __forceinline__ float dpp_ror(float v) { return __builtin_bit_cast(float, __builtin_amdgcn_update_dpp(0, __builtin_bit_cast(int, v), 0x120 + N, 0xf, 0xf, false)); }
; __device__ __forceinline__ unsigned cvt_pk_bf16(float lo, float hi) { unsigned r; asm volatile("v_cvt_pk_bf16_f32 %0, %1, %2" : "=v"(r) : "v"(lo), "v"(hi)); return r; }
;     __device__ __forceinline__ void run(const f32x4 (&acc)[2][2][4][2], const Unit& u, int wr, int wc, int fr, int fq, PG8_LAS unsigned char* lds, int buf) const {
;     ...
;                     for (int eh = 0; eh < 2; ++eh) { const int e = 2 * ep + eh;
;                         float R[4], L[4];
; #pragma unroll
;                         for (int m = 0; m < 4; ++m) { R[m] = dpp_ror<1>(acc[ai][1][m][n][e]); L[m] = dpp_ror<15>(acc[ai][1][m][n][e]); }
; #pragma unroll
;                         for (int m = 0; m < 4; ++m) {
;                             const float up = (fr == 0) ? R[m > 0 ? m - 1 : 0] : R[m];
;                             const float dn = (fr == 15) ? L[m < 3 ? m + 1 : 3] : L[m];
;                             xv[m][eh] = up * w0[n][e] + acc[ai][1][m][n][e] * w1[n][e] + dn * w2[n][e] + bb[n][e];
;                         } }
; #pragma unroll
;                     for (int m = 0; m < 4; ++m) {
;                         const float p0 = __builtin_amdgcn_exp2f(fminf(-1.4426950408889634f * xv[m][0], 60.0f)) + 1.0f, p1 = __builtin_amdgcn_exp2f(fminf(-1.4426950408889634f * xv[m][1], 60.0f)) + 1.0f;
;                         const float r = __builtin_amdgcn_rcpf(p0 * p1);
;                         const bool edge = (m == 0 && fr == 0) || (m == 3 && fr == 15);
;                         ov[m][0] = edge ? acc[ai][0][m][n][2 * ep] : xv[m][0] * (r * p1) * acc[ai][0][m][n][2 * ep];
;                         ov[m][1] = edge ? acc[ai][0][m][n][2 * ep + 1] : xv[m][1] * (r * p0) * acc[ai][0][m][n][2 * ep + 1];
;                     }
; #pragma unroll
;                     for (int m = 0; m < 4; ++m) op[m][n][ep] = cvt_pk_bf16(ov[m][0], ov[m][1]);
	v_mov_b32_dpp v203, v89 row_ror:1 row_mask:0xf bank_mask:0xf
	v_mov_b32_dpp v204, v96 row_ror:15 row_mask:0xf bank_mask:0xf
	v_mov_b32_dpp v205, v97 row_ror:15 row_mask:0xf bank_mask:0xf
	v_mov_b32_dpp v208, v160 row_ror:15 row_mask:0xf bank_mask:0xf
	v_mov_b32_dpp v209, v161 row_ror:15 row_mask:0xf bank_mask:0xf
	v_mov_b32_dpp v210, v156 row_ror:15 row_mask:0xf bank_mask:0xf
	v_mov_b32_dpp v211, v157 row_ror:15 row_mask:0xf bank_mask:0xf
	v_mov_b32_dpp v214, v88 row_ror:15 row_mask:0xf bank_mask:0xf
	v_mov_b32_dpp v215, v89 row_ror:15 row_mask:0xf bank_mask:0xf
	v_cndmask_b32_e64 v202, v202, v200, s[48:49]
	v_cndmask_b32_e64 v203, v203, v201, s[48:49]
	v_cndmask_b32_e64 v200, v200, v198, s[48:49]
	v_cndmask_b32_e64 v201, v201, v199, s[48:49]
	v_cndmask_b32_e64 v198, v198, v196, s[48:49]
	v_cndmask_b32_e64 v199, v199, v197, s[48:49]
	v_cndmask_b32_e64 v204, v204, v208, s[50:51]
	v_cndmask_b32_e64 v205, v205, v209, s[50:51]
	v_cndmask_b32_e64 v208, v208, v210, s[50:51]
	v_cndmask_b32_e64 v209, v209, v211, s[50:51]
	v_cndmask_b32_e64 v210, v210, v214, s[50:51]
	v_cndmask_b32_e64 v211, v211, v215, s[50:51]
	v_pk_fma_f32 v[204:205], v[204:205], v[136:137], v[132:133]
	v_pk_fma_f32 v[208:209], v[208:209], v[136:137], v[132:133]
	v_pk_fma_f32 v[210:211], v[210:211], v[136:137], v[132:133]
	v_pk_fma_f32 v[214:215], v[214:215], v[136:137], v[132:133]
	v_pk_fma_f32 v[204:205], v[96:97], v[128:129], v[204:205]
	v_pk_fma_f32 v[208:209], v[160:161], v[128:129], v[208:209]
	v_pk_fma_f32 v[210:211], v[156:157], v[128:129], v[210:211]
	v_pk_fma_f32 v[214:215], v[88:89], v[128:129], v[214:215]
	v_pk_fma_f32 v[204:205], v[196:197], v[124:125], v[204:205]
	v_pk_fma_f32 v[208:209], v[198:199], v[124:125], v[208:209]
	v_pk_fma_f32 v[210:211], v[200:201], v[124:125], v[210:211]
	v_pk_fma_f32 v[214:215], v[202:203], v[124:125], v[214:215]
	v_pk_mul_f32 v[196:197], v[204:205], s[52:53]
	v_pk_mul_f32 v[198:199], v[208:209], s[52:53]
	v_pk_mul_f32 v[200:201], v[210:211], s[52:53]
	v_pk_mul_f32 v[202:203], v[214:215], s[52:53]
	v_min_f32_e32 v196, 0x42700000, v196
	v_min_f32_e32 v197, 0x42700000, v197
	v_min_f32_e32 v198, 0x42700000, v198
	v_min_f32_e32 v199, 0x42700000, v199
	v_min_f32_e32 v200, 0x42700000, v200
	v_min_f32_e32 v201, 0x42700000, v201
	v_min_f32_e32 v202, 0x42700000, v202
	v_min_f32_e32 v203, 0x42700000, v203
	v_exp_f32_e32 v196, v196
	v_exp_f32_e32 v197, v197
	v_exp_f32_e32 v198, v198
	v_exp_f32_e32 v199, v199
	v_exp_f32_e32 v200, v200
	v_exp_f32_e32 v201, v201
	v_exp_f32_e32 v202, v202
	v_exp_f32_e32 v203, v203
	v_pk_add_f32 v[196:197], v[196:197], 1.0 op_sel_hi:[1,0]
	v_pk_add_f32 v[198:199], v[198:199], 1.0 op_sel_hi:[1,0]
	v_pk_add_f32 v[200:201], v[200:201], 1.0 op_sel_hi:[1,0]
	v_pk_add_f32 v[202:203], v[202:203], 1.0 op_sel_hi:[1,0]
	v_mul_f32_e32 v216, v196, v197
	v_mul_f32_e32 v217, v198, v199
	v_mul_f32_e32 v218, v200, v201
	v_mul_f32_e32 v219, v202, v203
	v_rcp_f32_e32 v216, v216
	v_rcp_f32_e32 v217, v217
	v_rcp_f32_e32 v218, v218
	v_rcp_f32_e32 v219, v219
	v_pk_mul_f32 v[196:197], v[196:197], v[216:217] op_sel:[1,0] op_sel_hi:[0,0]
	v_pk_mul_f32 v[198:199], v[198:199], v[216:217] op_sel:[1,1] op_sel_hi:[0,1]
	v_pk_mul_f32 v[200:201], v[200:201], v[218:219] op_sel:[1,0] op_sel_hi:[0,0]
	v_pk_mul_f32 v[202:203], v[202:203], v[218:219] op_sel:[1,1] op_sel_hi:[0,1]
	v_pk_mul_f32 v[204:205], v[204:205], v[196:197]
	v_pk_mul_f32 v[208:209], v[208:209], v[198:199]
	v_pk_mul_f32 v[210:211], v[210:211], v[200:201]
	v_pk_mul_f32 v[214:215], v[214:215], v[202:203]
	v_pk_mul_f32 v[204:205], v[204:205], v[152:153]
	v_pk_mul_f32 v[208:209], v[208:209], v[148:149]
	v_pk_mul_f32 v[210:211], v[210:211], v[144:145]
	v_pk_mul_f32 v[214:215], v[214:215], v[140:141]
	v_cndmask_b32_e64 v204, v204, v152, s[48:49]
	v_cndmask_b32_e64 v205, v205, v153, s[48:49]
	v_cndmask_b32_e64 v214, v214, v140, s[50:51]
	v_cndmask_b32_e64 v215, v215, v141, s[50:51]
	v_cvt_pk_bf16_f32 v151, v204, v205
	v_cvt_pk_bf16_f32 v147, v208, v209
	v_cvt_pk_bf16_f32 v143, v210, v211
	v_cvt_pk_bf16_f32 v139, v214, v215
	v_mov_b32_dpp v196, v90 row_ror:1 row_mask:0xf bank_mask:0xf
	v_mov_b32_dpp v197, v91 row_ror:1 row_mask:0xf bank_mask:0xf
	v_mov_b32_dpp v198, v118 row_ror:1 row_mask:0xf bank_mask:0xf
	v_mov_b32_dpp v199, v119 row_ror:1 row_mask:0xf bank_mask:0xf
	v_mov_b32_dpp v200, v114 row_ror:1 row_mask:0xf bank_mask:0xf
	v_mov_b32_dpp v201, v115 row_ror:1 row_mask:0xf bank_mask:0xf
	v_mov_b32_dpp v202, v82 row_ror:1 row_mask:0xf bank_mask:0xf
	v_mov_b32_dpp v203, v83 row_ror:1 row_mask:0xf bank_mask:0xf
	v_mov_b32_dpp v204, v90 row_ror:15 row_mask:0xf bank_mask:0xf
	v_mov_b32_dpp v205, v91 row_ror:15 row_mask:0xf bank_mask:0xf
	v_mov_b32_dpp v208, v118 row_ror:15 row_mask:0xf bank_mask:0xf
	v_mov_b32_dpp v209, v119 row_ror:15 row_mask:0xf bank_mask:0xf
	v_mov_b32_dpp v210, v114 row_ror:15 row_mask:0xf bank_mask:0xf
	v_mov_b32_dpp v211, v115 row_ror:15 row_mask:0xf bank_mask:0xf
	v_mov_b32_dpp v214, v82 row_ror:15 row_mask:0xf bank_mask:0xf
	v_mov_b32_dpp v215, v83 row_ror:15 row_mask:0xf bank_mask:0xf
	v_cndmask_b32_e64 v202, v202, v200, s[48:49]
	v_cndmask_b32_e64 v203, v203, v201, s[48:49]
	v_cndmask_b32_e64 v200, v200, v198, s[48:49]
	v_cndmask_b32_e64 v201, v201, v199, s[48:49]
	v_cndmask_b32_e64 v198, v198, v196, s[48:49]
	v_cndmask_b32_e64 v199, v199, v197, s[48:49]
	v_cndmask_b32_e64 v204, v204, v208, s[50:51]
	v_cndmask_b32_e64 v205, v205, v209, s[50:51]
	v_cndmask_b32_e64 v208, v208, v210, s[50:51]
	v_cndmask_b32_e64 v209, v209, v211, s[50:51]
	v_cndmask_b32_e64 v210, v210, v214, s[50:51]
	v_cndmask_b32_e64 v211, v211, v215, s[50:51]
	v_pk_fma_f32 v[204:205], v[204:205], v[78:79], v[70:71]
; template <int N> __device__ __forceinline__ float dpp_ror(float v) { return __builtin_bit_cast(float, __builtin_amdgcn_update_dpp(0, __builtin_bit_cast(int, v), 0x120 + N, 0xf, 0xf, false)); }
; __device__ __forceinline__ unsigned cvt_pk_bf16(float lo, float hi) { unsigned r; asm volatile("v_cvt_pk_bf16_f32 %0, %1, %2" : "=v"(r) : "v"(lo), "v"(hi)); return r; }
;     __device__ __forceinline__ void run(const f32x4 (&acc)[2][2][4][2], const Unit& u, int wr, int wc, int fr, int fq, PG8_LAS unsigned char* lds, int buf) const {
;     ...
;                     for (int eh = 0; eh < 2; ++eh) { const int e = 2 * ep + eh;
;                         float R[4], L[4];
; #pragma unroll
;                         for (int m = 0; m < 4; ++m) { R[m] = dpp_ror<1>(acc[ai][1][m][n][e]); L[m] = dpp_ror<15>(acc[ai][1][m][n][e]); }
; #pragma unroll
;                         for (int m = 0; m < 4; ++m) {
;                             const float up = (fr == 0) ? R[m > 0 ? m - 1 : 0] : R[m];
;                             const float dn = (fr == 15) ? L[m < 3 ? m + 1 : 3] : L[m];
;                             xv[m][eh] = up * w0[n][e] + acc[ai][1][m][n][e] * w1[n][e] + dn * w2[n][e] + bb[n][e];
;                         } }
; #pragma unroll
;                     for (int m = 0; m < 4; ++m) {
;                         const float p0 = __builtin_amdgcn_exp2f(fminf(-1.4426950408889634f * xv[m][0], 60.0f)) + 1.0f, p1 = __builtin_amdgcn_exp2f(fminf(-1.4426950408889634f * xv[m][1], 60.0f)) + 1.0f;
;                         const float r = __builtin_amdgcn_rcpf(p0 * p1);
;                         const bool edge = (m == 0 && fr == 0) || (m == 3 && fr == 15);
;                         ov[m][0] = edge ? acc[ai][0][m][n][2 * ep] : xv[m][0] * (r * p1) * acc[ai][0][m][n][2 * ep];
;                         ov[m][1] = edge ? acc[ai][0][m][n][2 * ep + 1] : xv[m][1] * (r * p0) * acc[ai][0][m][n][2 * ep + 1];
;                     }
; #pragma unroll
;                     for (int m = 0; m < 4; ++m) op[m][n][ep] = cvt_pk_bf16(ov[m][0], ov[m][1]);
	v_pk_fma_f32 v[208:209], v[208:209], v[78:79], v[70:71]
	v_pk_fma_f32 v[210:211], v[210:211], v[78:79], v[70:71]
	v_pk_fma_f32 v[214:215], v[214:215], v[78:79], v[70:71]
	v_pk_fma_f32 v[204:205], v[90:91], v[74:75], v[204:205]
	v_pk_fma_f32 v[208:209], v[118:119], v[74:75], v[208:209]
	v_pk_fma_f32 v[210:211], v[114:115], v[74:75], v[210:211]
	v_pk_fma_f32 v[214:215], v[82:83], v[74:75], v[214:215]
	v_pk_fma_f32 v[204:205], v[196:197], v[66:67], v[204:205]
	v_pk_fma_f32 v[208:209], v[198:199], v[66:67], v[208:209]
	v_pk_fma_f32 v[210:211], v[200:201], v[66:67], v[210:211]
	v_pk_fma_f32 v[214:215], v[202:203], v[66:67], v[214:215]
	v_pk_mul_f32 v[196:197], v[204:205], s[52:53]
	v_pk_mul_f32 v[198:199], v[208:209], s[52:53]
	v_pk_mul_f32 v[200:201], v[210:211], s[52:53]
	v_pk_mul_f32 v[202:203], v[214:215], s[52:53]
	v_min_f32_e32 v196, 0x42700000, v196
	v_min_f32_e32 v197, 0x42700000, v197
	v_min_f32_e32 v198, 0x42700000, v198
	v_min_f32_e32 v199, 0x42700000, v199
	v_min_f32_e32 v200, 0x42700000, v200
	v_min_f32_e32 v201, 0x42700000, v201
	v_min_f32_e32 v202, 0x42700000, v202
	v_min_f32_e32 v203, 0x42700000, v203
	v_exp_f32_e32 v196, v196
	v_exp_f32_e32 v197, v197
	v_exp_f32_e32 v198, v198
	v_exp_f32_e32 v199, v199
	v_exp_f32_e32 v200, v200
	v_exp_f32_e32 v201, v201
	v_exp_f32_e32 v202, v202
	v_exp_f32_e32 v203, v203
	v_pk_add_f32 v[196:197], v[196:197], 1.0 op_sel_hi:[1,0]
	v_pk_add_f32 v[198:199], v[198:199], 1.0 op_sel_hi:[1,0]
	v_pk_add_f32 v[200:201], v[200:201], 1.0 op_sel_hi:[1,0]
	v_pk_add_f32 v[202:203], v[202:203], 1.0 op_sel_hi:[1,0]
	v_mul_f32_e32 v216, v196, v197
	v_mul_f32_e32 v217, v198, v199
	v_mul_f32_e32 v218, v200, v201
	v_mul_f32_e32 v219, v202, v203
	v_rcp_f32_e32 v216, v216
	v_rcp_f32_e32 v217, v217
	v_rcp_f32_e32 v218, v218
	v_rcp_f32_e32 v219, v219
	v_pk_mul_f32 v[196:197], v[196:197], v[216:217] op_sel:[1,0] op_sel_hi:[0,0]
	v_pk_mul_f32 v[198:199], v[198:199], v[216:217] op_sel:[1,1] op_sel_hi:[0,1]
	v_pk_mul_f32 v[200:201], v[200:201], v[218:219] op_sel:[1,0] op_sel_hi:[0,0]
	v_pk_mul_f32 v[202:203], v[202:203], v[218:219] op_sel:[1,1] op_sel_hi:[0,1]
	v_pk_mul_f32 v[204:205], v[204:205], v[196:197]
	v_pk_mul_f32 v[208:209], v[208:209], v[198:199]
	v_pk_mul_f32 v[210:211], v[210:211], v[200:201]
	v_pk_mul_f32 v[214:215], v[214:215], v[202:203]
	v_pk_mul_f32 v[204:205], v[204:205], v[110:111]
	v_pk_mul_f32 v[208:209], v[208:209], v[106:107]
	v_pk_mul_f32 v[210:211], v[210:211], v[102:103]
	v_pk_mul_f32 v[214:215], v[214:215], v[98:99]
	v_cndmask_b32_e64 v204, v204, v110, s[48:49]
	v_cndmask_b32_e64 v205, v205, v111, s[48:49]
	v_cndmask_b32_e64 v214, v214, v98, s[50:51]
	v_cndmask_b32_e64 v215, v215, v99, s[50:51]
	v_cvt_pk_bf16_f32 v152, v204, v205
	v_cvt_pk_bf16_f32 v148, v208, v209
	v_cvt_pk_bf16_f32 v144, v210, v211
	v_cvt_pk_bf16_f32 v140, v214, v215
	v_mov_b32_dpp v196, v92 row_ror:1 row_mask:0xf bank_mask:0xf
	v_mov_b32_dpp v197, v93 row_ror:1 row_mask:0xf bank_mask:0xf
	v_mov_b32_dpp v198, v120 row_ror:1 row_mask:0xf bank_mask:0xf
	v_mov_b32_dpp v199, v121 row_ror:1 row_mask:0xf bank_mask:0xf
	v_mov_b32_dpp v200, v116 row_ror:1 row_mask:0xf bank_mask:0xf
	v_mov_b32_dpp v201, v117 row_ror:1 row_mask:0xf bank_mask:0xf
	v_mov_b32_dpp v202, v84 row_ror:1 row_mask:0xf bank_mask:0xf
	v_mov_b32_dpp v203, v85 row_ror:1 row_mask:0xf bank_mask:0xf
	v_mov_b32_dpp v204, v92 row_ror:15 row_mask:0xf bank_mask:0xf
	v_mov_b32_dpp v205, v93 row_ror:15 row_mask:0xf bank_mask:0xf
	v_mov_b32_dpp v208, v120 row_ror:15 row_mask:0xf bank_mask:0xf
	v_mov_b32_dpp v209, v121 row_ror:15 row_mask:0xf bank_mask:0xf
	v_mov_b32_dpp v210, v116 row_ror:15 row_mask:0xf bank_mask:0xf
	v_mov_b32_dpp v211, v117 row_ror:15 row_mask:0xf bank_mask:0xf
	v_mov_b32_dpp v214, v84 row_ror:15 row_mask:0xf bank_mask:0xf
	v_mov_b32_dpp v215, v85 row_ror:15 row_mask:0xf bank_mask:0xf
	v_cndmask_b32_e64 v202, v202, v200, s[48:49]
	v_cndmask_b32_e64 v203, v203, v201, s[48:49]
	v_cndmask_b32_e64 v200, v200, v198, s[48:49]
	v_cndmask_b32_e64 v201, v201, v199, s[48:49]
	v_cndmask_b32_e64 v198, v198, v196, s[48:49]
	v_cndmask_b32_e64 v199, v199, v197, s[48:49]
	v_cndmask_b32_e64 v204, v204, v208, s[50:51]
	v_cndmask_b32_e64 v205, v205, v209, s[50:51]
	v_cndmask_b32_e64 v208, v208, v210, s[50:51]
;     __device__ __forceinline__ void run(const f32x4 (&acc)[2][2][4][2], const Unit& u, int wr, int wc, int fr, int fq, PG8_LAS unsigned char* lds, int buf) const {
;     ...
;                     for (int eh = 0; eh < 2; ++eh) { const int e = 2 * ep + eh;
;                         float R[4], L[4];
; #pragma unroll
;                         for (int m = 0; m < 4; ++m) { R[m] = dpp_ror<1>(acc[ai][1][m][n][e]); L[m] = dpp_ror<15>(acc[ai][1][m][n][e]); }
; #pragma unroll
;                         for (int m = 0; m < 4; ++m) {
;                             const float up = (fr == 0) ? R[m > 0 ? m - 1 : 0] : R[m];
;                             const float dn = (fr == 15) ? L[m < 3 ? m + 1 : 3] : L[m];
;                             xv[m][eh] = up * w0[n][e] + acc[ai][1][m][n][e] * w1[n][e] + dn * w2[n][e] + bb[n][e];
;                         } }
; #pragma unroll
;                     for (int m = 0; m < 4; ++m) {
;                         const float p0 = __builtin_amdgcn_exp2f(fminf(-1.4426950408889634f * xv[m][0], 60.0f)) + 1.0f, p1 = __builtin_amdgcn_exp2f(fminf(-1.4426950408889634f * xv[m][1], 60.0f)) + 1.0f;
;                         const float r = __builtin_amdgcn_rcpf(p0 * p1);
;                         const bool edge = (m == 0 && fr == 0) || (m == 3 && fr == 15);
;                         ov[m][0] = edge ? acc[ai][0][m][n][2 * ep] : xv[m][0] * (r * p1) * acc[ai][0][m][n][2 * ep];
;                         ov[m][1] = edge ? acc[ai][0][m][n][2 * ep + 1] : xv[m][1] * (r * p0) * acc[ai][0][m][n][2 * ep + 1];
;                     }
; #pragma unroll
;                     for (int m = 0; m < 4; ++m) op[m][n][ep] = cvt_pk_bf16(ov[m][0], ov[m][1]);
;                     __builtin_amdgcn_sched_barrier(0);
;                 }
; #pragma unroll
;             for (int m = 0; m < 4; ++m) {
;                 u32x4 w; w.x = op[m][0][0]; w.y = op[m][0][1]; w.z = op[m][1][0]; w.w = op[m][1][1];
;                 *(u32x4*)(ACT + (size_t)(row0 + ai * HALF + m * 16) * 5632 + ch0) = w;
;             }
;             const int grp = u.pm * 4 + ai * 2 + wr;
;             if (fr <= 1) { const f32x4 g0 = acc[ai][1][0][0], g1 = acc[ai][1][0][1];
;                 u32x4 w; w.x = cvt_pk_bf16(g0[0], g0[1]); w.y = cvt_pk_bf16(g0[2], g0[3]); w.z = cvt_pk_bf16(g1[0], g1[1]); w.w = cvt_pk_bf16(g1[2], g1[3]);
;                 *(u32x4*)(GB + ((size_t)(grp * 4 + fr)) * 5632 + ch0) = w; }
	v_cndmask_b32_e64 v209, v209, v211, s[50:51]
	v_cndmask_b32_e64 v210, v210, v214, s[50:51]
	v_cndmask_b32_e64 v211, v211, v215, s[50:51]
	v_pk_fma_f32 v[204:205], v[204:205], v[80:81], v[72:73]
	v_pk_fma_f32 v[208:209], v[208:209], v[80:81], v[72:73]
	v_pk_fma_f32 v[210:211], v[210:211], v[80:81], v[72:73]
	v_pk_fma_f32 v[214:215], v[214:215], v[80:81], v[72:73]
	v_pk_fma_f32 v[204:205], v[92:93], v[76:77], v[204:205]
	v_pk_fma_f32 v[208:209], v[120:121], v[76:77], v[208:209]
	v_pk_fma_f32 v[210:211], v[116:117], v[76:77], v[210:211]
	v_pk_fma_f32 v[214:215], v[84:85], v[76:77], v[214:215]
	v_pk_fma_f32 v[204:205], v[196:197], v[68:69], v[204:205]
	v_pk_fma_f32 v[208:209], v[198:199], v[68:69], v[208:209]
	v_pk_fma_f32 v[210:211], v[200:201], v[68:69], v[210:211]
	v_pk_fma_f32 v[214:215], v[202:203], v[68:69], v[214:215]
	v_pk_mul_f32 v[196:197], v[204:205], s[52:53]
	v_pk_mul_f32 v[198:199], v[208:209], s[52:53]
	v_pk_mul_f32 v[200:201], v[210:211], s[52:53]
	v_pk_mul_f32 v[202:203], v[214:215], s[52:53]
	v_min_f32_e32 v196, 0x42700000, v196
	v_min_f32_e32 v197, 0x42700000, v197
	v_min_f32_e32 v198, 0x42700000, v198
	v_min_f32_e32 v199, 0x42700000, v199
	v_min_f32_e32 v200, 0x42700000, v200
	v_min_f32_e32 v201, 0x42700000, v201
	v_min_f32_e32 v202, 0x42700000, v202
	v_min_f32_e32 v203, 0x42700000, v203
	v_exp_f32_e32 v196, v196
	v_exp_f32_e32 v197, v197
	v_exp_f32_e32 v198, v198
	v_exp_f32_e32 v199, v199
	v_exp_f32_e32 v200, v200
	v_exp_f32_e32 v201, v201
	v_exp_f32_e32 v202, v202
	v_exp_f32_e32 v203, v203
	v_pk_add_f32 v[196:197], v[196:197], 1.0 op_sel_hi:[1,0]
	v_pk_add_f32 v[198:199], v[198:199], 1.0 op_sel_hi:[1,0]
	v_pk_add_f32 v[200:201], v[200:201], 1.0 op_sel_hi:[1,0]
	v_pk_add_f32 v[202:203], v[202:203], 1.0 op_sel_hi:[1,0]
	v_mul_f32_e32 v216, v196, v197
	v_mul_f32_e32 v217, v198, v199
	v_mul_f32_e32 v218, v200, v201
	v_mul_f32_e32 v219, v202, v203
	v_rcp_f32_e32 v216, v216
	v_rcp_f32_e32 v217, v217
	v_rcp_f32_e32 v218, v218
	v_rcp_f32_e32 v219, v219
	v_pk_mul_f32 v[196:197], v[196:197], v[216:217] op_sel:[1,0] op_sel_hi:[0,0]
	v_pk_mul_f32 v[198:199], v[198:199], v[216:217] op_sel:[1,1] op_sel_hi:[0,1]
	v_pk_mul_f32 v[200:201], v[200:201], v[218:219] op_sel:[1,0] op_sel_hi:[0,0]
	v_pk_mul_f32 v[202:203], v[202:203], v[218:219] op_sel:[1,1] op_sel_hi:[0,1]
	v_pk_mul_f32 v[204:205], v[204:205], v[196:197]
	v_pk_mul_f32 v[208:209], v[208:209], v[198:199]
	v_pk_mul_f32 v[210:211], v[210:211], v[200:201]
	v_pk_mul_f32 v[214:215], v[214:215], v[202:203]
	v_pk_mul_f32 v[204:205], v[204:205], v[112:113]
	v_pk_mul_f32 v[208:209], v[208:209], v[108:109]
	v_pk_mul_f32 v[210:211], v[210:211], v[104:105]
	v_pk_mul_f32 v[214:215], v[214:215], v[100:101]
	v_cndmask_b32_e64 v204, v204, v112, s[48:49]
	v_cndmask_b32_e64 v205, v205, v113, s[48:49]
	v_cndmask_b32_e64 v214, v214, v100, s[50:51]
	v_cndmask_b32_e64 v215, v215, v101, s[50:51]
	v_cvt_pk_bf16_f32 v153, v204, v205
	v_cvt_pk_bf16_f32 v149, v208, v209
	v_cvt_pk_bf16_f32 v145, v210, v211
	v_cvt_pk_bf16_f32 v141, v214, v215
	v_mov_b64_e32 v[102:103], s[26:27]
	s_movk_i32 s31, 0x2c00
	v_mad_i64_i32 v[104:105], s[48:49], v194, s31, v[102:103]
	v_lshlrev_b64 v[100:101], 1, v[188:189]
	v_lshl_add_u64 v[104:105], v[104:105], 0, v[100:101]
	v_or_b32_e32 v98, 16, v194
	global_store_dwordx4 v[104:105], v[150:153], off
	v_mad_i64_i32 v[104:105], s[48:49], v98, s31, v[102:103]
	v_lshl_add_u64 v[104:105], v[104:105], 0, v[100:101]
	v_or_b32_e32 v98, 32, v194
	global_store_dwordx4 v[104:105], v[146:149], off
	v_mad_i64_i32 v[104:105], s[48:49], v98, s31, v[102:103]
	v_or_b32_e32 v98, 48, v194
	v_mad_i64_i32 v[102:103], s[48:49], v98, s31, v[102:103]
	v_lshl_add_u64 v[104:105], v[104:105], 0, v[100:101]
	v_lshl_add_u64 v[102:103], v[102:103], 0, v[100:101]
	global_store_dwordx4 v[104:105], v[142:145], off
	global_store_dwordx4 v[102:103], v[138:141], off
	s_and_saveexec_b64 s[48:49], s[38:39]
	s_cbranch_execz .LBB0_1164
	v_cvt_pk_bf16_f32 v94, v94, v95
	v_cvt_pk_bf16_f32 v95, v96, v97
	v_cvt_pk_bf16_f32 v96, v90, v91
	v_cvt_pk_bf16_f32 v97, v92, v93
	v_lshl_or_b32 v92, s23, 2, v21
	v_mov_b64_e32 v[90:91], s[36:37]
	v_mad_i64_i32 v[90:91], s[50:51], v92, s31, v[90:91]
	v_lshl_add_u64 v[90:91], v[188:189], 1, v[90:91]
	global_store_dwordx4 v[90:91], v[94:97], off

; template <int N> __device__ __forceinline__ float dpp_ror(float v) { return __builtin_bit_cast(float, __builtin_amdgcn_update_dpp(0, __builtin_bit_cast(int, v), 0x120 + N, 0xf, 0xf, false)); }
; __device__ __forceinline__ unsigned cvt_pk_bf16(float lo, float hi) { unsigned r; asm volatile("v_cvt_pk_bf16_f32 %0, %1, %2" : "=v"(r) : "v"(lo), "v"(hi)); return r; }
;     __device__ __forceinline__ void run(const f32x4 (&acc)[2][2][4][2], const Unit& u, int wr, int wc, int fr, int fq, PG8_LAS unsigned char* lds, int buf) const {
;     ...
;                     for (int eh = 0; eh < 2; ++eh) { const int e = 2 * ep + eh;
;                         float R[4], L[4];
; #pragma unroll
;                         for (int m = 0; m < 4; ++m) { R[m] = dpp_ror<1>(acc[ai][1][m][n][e]); L[m] = dpp_ror<15>(acc[ai][1][m][n][e]); }
; #pragma unroll
;                         for (int m = 0; m < 4; ++m) {
;                             const float up = (fr == 0) ? R[m > 0 ? m - 1 : 0] : R[m];
;                             const float dn = (fr == 15) ? L[m < 3 ? m + 1 : 3] : L[m];
;                             xv[m][eh] = up * w0[n][e] + acc[ai][1][m][n][e] * w1[n][e] + dn * w2[n][e] + bb[n][e];
;                         } }
; #pragma unroll
;                     for (int m = 0; m < 4; ++m) {
;                         const float p0 = __builtin_amdgcn_exp2f(fminf(-1.4426950408889634f * xv[m][0], 60.0f)) + 1.0f, p1 = __builtin_amdgcn_exp2f(fminf(-1.4426950408889634f * xv[m][1], 60.0f)) + 1.0f;
;                         const float r = __builtin_amdgcn_rcpf(p0 * p1);
;                         const bool edge = (m == 0 && fr == 0) || (m == 3 && fr == 15);
;                         ov[m][0] = edge ? acc[ai][0][m][n][2 * ep] : xv[m][0] * (r * p1) * acc[ai][0][m][n][2 * ep];
;                         ov[m][1] = edge ? acc[ai][0][m][n][2 * ep + 1] : xv[m][1] * (r * p0) * acc[ai][0][m][n][2 * ep + 1];
;                     }
; #pragma unroll
;                     for (int m = 0; m < 4; ++m) op[m][n][ep] = cvt_pk_bf16(ov[m][0], ov[m][1]);
.LBB0_1166:
	s_or_b64 exec, exec, s[48:49]
	v_cmp_eq_u32_e64 s[48:49], 0, v21
	v_cmp_eq_u32_e64 s[50:51], 15, v21
	s_mov_b32 s52, 0xbfb8aa3b
	s_mov_b32 s53, 0xbfb8aa3b
	v_mov_b32_dpp v196, v12 row_ror:1 row_mask:0xf bank_mask:0xf
	v_mov_b32_dpp v197, v13 row_ror:1 row_mask:0xf bank_mask:0xf
	v_mov_b32_dpp v198, v62 row_ror:1 row_mask:0xf bank_mask:0xf
	v_mov_b32_dpp v199, v63 row_ror:1 row_mask:0xf bank_mask:0xf
	v_mov_b32_dpp v200, v58 row_ror:1 row_mask:0xf bank_mask:0xf
	v_mov_b32_dpp v201, v59 row_ror:1 row_mask:0xf bank_mask:0xf
	v_mov_b32_dpp v202, v4 row_ror:1 row_mask:0xf bank_mask:0xf
	v_mov_b32_dpp v203, v5 row_ror:1 row_mask:0xf bank_mask:0xf
	v_mov_b32_dpp v204, v12 row_ror:15 row_mask:0xf bank_mask:0xf
	v_mov_b32_dpp v205, v13 row_ror:15 row_mask:0xf bank_mask:0xf
	v_mov_b32_dpp v208, v62 row_ror:15 row_mask:0xf bank_mask:0xf
	v_mov_b32_dpp v209, v63 row_ror:15 row_mask:0xf bank_mask:0xf
	v_mov_b32_dpp v210, v58 row_ror:15 row_mask:0xf bank_mask:0xf
	v_mov_b32_dpp v211, v59 row_ror:15 row_mask:0xf bank_mask:0xf
	v_mov_b32_dpp v214, v4 row_ror:15 row_mask:0xf bank_mask:0xf
	v_mov_b32_dpp v215, v5 row_ror:15 row_mask:0xf bank_mask:0xf
	v_cndmask_b32_e64 v202, v202, v200, s[48:49]
	v_cndmask_b32_e64 v203, v203, v201, s[48:49]
	v_cndmask_b32_e64 v200, v200, v198, s[48:49]
	v_cndmask_b32_e64 v201, v201, v199, s[48:49]
	v_cndmask_b32_e64 v198, v198, v196, s[48:49]
	v_cndmask_b32_e64 v199, v199, v197, s[48:49]
	v_cndmask_b32_e64 v204, v204, v208, s[50:51]
	v_cndmask_b32_e64 v205, v205, v209, s[50:51]
	v_cndmask_b32_e64 v208, v208, v210, s[50:51]
	v_cndmask_b32_e64 v209, v209, v211, s[50:51]
	v_cndmask_b32_e64 v210, v210, v214, s[50:51]
	v_cndmask_b32_e64 v211, v211, v215, s[50:51]
	v_pk_fma_f32 v[204:205], v[204:205], v[134:135], v[130:131]
	v_pk_fma_f32 v[208:209], v[208:209], v[134:135], v[130:131]
	v_pk_fma_f32 v[210:211], v[210:211], v[134:135], v[130:131]
	v_pk_fma_f32 v[214:215], v[214:215], v[134:135], v[130:131]
	v_pk_fma_f32 v[204:205], v[12:13], v[126:127], v[204:205]
	v_pk_fma_f32 v[208:209], v[62:63], v[126:127], v[208:209]
	v_pk_fma_f32 v[210:211], v[58:59], v[126:127], v[210:211]
	v_pk_fma_f32 v[214:215], v[4:5], v[126:127], v[214:215]
	v_pk_fma_f32 v[204:205], v[196:197], v[122:123], v[204:205]
	v_pk_fma_f32 v[208:209], v[198:199], v[122:123], v[208:209]
	v_pk_fma_f32 v[210:211], v[200:201], v[122:123], v[210:211]
	v_pk_fma_f32 v[214:215], v[202:203], v[122:123], v[214:215]
	v_pk_mul_f32 v[196:197], v[204:205], s[52:53]
	v_pk_mul_f32 v[198:199], v[208:209], s[52:53]
	v_pk_mul_f32 v[200:201], v[210:211], s[52:53]
	v_pk_mul_f32 v[202:203], v[214:215], s[52:53]
	v_min_f32_e32 v196, 0x42700000, v196
	v_min_f32_e32 v197, 0x42700000, v197
	v_min_f32_e32 v198, 0x42700000, v198
	v_min_f32_e32 v199, 0x42700000, v199
	v_min_f32_e32 v200, 0x42700000, v200
	v_min_f32_e32 v201, 0x42700000, v201
	v_min_f32_e32 v202, 0x42700000, v202
	v_min_f32_e32 v203, 0x42700000, v203
	v_exp_f32_e32 v196, v196
	v_exp_f32_e32 v197, v197
	v_exp_f32_e32 v198, v198
	v_exp_f32_e32 v199, v199
	v_exp_f32_e32 v200, v200
	v_exp_f32_e32 v201, v201
	v_exp_f32_e32 v202, v202
	v_exp_f32_e32 v203, v203
	v_pk_add_f32 v[196:197], v[196:197], 1.0 op_sel_hi:[1,0]
	v_pk_add_f32 v[198:199], v[198:199], 1.0 op_sel_hi:[1,0]
	v_pk_add_f32 v[200:201], v[200:201], 1.0 op_sel_hi:[1,0]
	v_pk_add_f32 v[202:203], v[202:203], 1.0 op_sel_hi:[1,0]
	v_mul_f32_e32 v216, v196, v197
	v_mul_f32_e32 v217, v198, v199
	v_mul_f32_e32 v218, v200, v201
	v_mul_f32_e32 v219, v202, v203
	v_rcp_f32_e32 v216, v216
	v_rcp_f32_e32 v217, v217
	v_rcp_f32_e32 v218, v218
	v_rcp_f32_e32 v219, v219
	v_pk_mul_f32 v[196:197], v[196:197], v[216:217] op_sel:[1,0] op_sel_hi:[0,0]
	v_pk_mul_f32 v[198:199], v[198:199], v[216:217] op_sel:[1,1] op_sel_hi:[0,1]
	v_pk_mul_f32 v[200:201], v[200:201], v[218:219] op_sel:[1,0] op_sel_hi:[0,0]
	v_pk_mul_f32 v[202:203], v[202:203], v[218:219] op_sel:[1,1] op_sel_hi:[0,1]
	v_pk_mul_f32 v[204:205], v[204:205], v[196:197]
	v_pk_mul_f32 v[208:209], v[208:209], v[198:199]
	v_pk_mul_f32 v[210:211], v[210:211], v[200:201]
	v_pk_mul_f32 v[214:215], v[214:215], v[202:203]
	v_pk_mul_f32 v[204:205], v[204:205], v[54:55]
	v_pk_mul_f32 v[208:209], v[208:209], v[50:51]
	v_pk_mul_f32 v[210:211], v[210:211], v[46:47]
	v_pk_mul_f32 v[214:215], v[214:215], v[42:43]
	v_cndmask_b32_e64 v204, v204, v54, s[48:49]
	v_cndmask_b32_e64 v205, v205, v55, s[48:49]
	v_cndmask_b32_e64 v214, v214, v42, s[50:51]
	v_cndmask_b32_e64 v215, v215, v43, s[50:51]
	v_cvt_pk_bf16_f32 v54, v204, v205
	v_cvt_pk_bf16_f32 v50, v208, v209
	v_cvt_pk_bf16_f32 v46, v210, v211
	v_cvt_pk_bf16_f32 v42, v214, v215
	v_mov_b32_dpp v196, v14 row_ror:1 row_mask:0xf bank_mask:0xf
	v_mov_b32_dpp v197, v15 row_ror:1 row_mask:0xf bank_mask:0xf
	v_mov_b32_dpp v198, v64 row_ror:1 row_mask:0xf bank_mask:0xf
	v_mov_b32_dpp v199, v65 row_ror:1 row_mask:0xf bank_mask:0xf
	v_mov_b32_dpp v200, v60 row_ror:1 row_mask:0xf bank_mask:0xf
	v_mov_b32_dpp v201, v61 row_ror:1 row_mask:0xf bank_mask:0xf
	v_mov_b32_dpp v202, v6 row_ror:1 row_mask:0xf bank_mask:0xf
	v_mov_b32_dpp v203, v7 row_ror:1 row_mask:0xf bank_mask:0xf
	v_mov_b32_dpp v204, v14 row_ror:15 row_mask:0xf bank_mask:0xf
	v_mov_b32_dpp v205, v15 row_ror:15 row_mask:0xf bank_mask:0xf
	v_mov_b32_dpp v208, v64 row_ror:15 row_mask:0xf bank_mask:0xf
	v_mov_b32_dpp v209, v65 row_ror:15 row_mask:0xf bank_mask:0xf
	v_mov_b32_dpp v210, v60 row_ror:15 row_mask:0xf bank_mask:0xf
	v_mov_b32_dpp v211, v61 row_ror:15 row_mask:0xf bank_mask:0xf
	v_mov_b32_dpp v214, v6 row_ror:15 row_mask:0xf bank_mask:0xf
	v_mov_b32_dpp v215, v7 row_ror:15 row_mask:0xf bank_mask:0xf
	v_cndmask_b32_e64 v202, v202, v200, s[48:49]
; template <int N> __device__ __forceinline__ float dpp_ror(float v) { return __builtin_bit_cast(float, __builtin_amdgcn_update_dpp(0, __builtin_bit_cast(int, v), 0x120 + N, 0xf, 0xf, false)); }
; __device__ __forceinline__ unsigned cvt_pk_bf16(float lo, float hi) { unsigned r; asm volatile("v_cvt_pk_bf16_f32 %0, %1, %2" : "=v"(r) : "v"(lo), "v"(hi)); return r; }
;     __device__ __forceinline__ void run(const f32x4 (&acc)[2][2][4][2], const Unit& u, int wr, int wc, int fr, int fq, PG8_LAS unsigned char* lds, int buf) const {
;     ...
;                     for (int eh = 0; eh < 2; ++eh) { const int e = 2 * ep + eh;
;                         float R[4], L[4];
; #pragma unroll
;                         for (int m = 0; m < 4; ++m) { R[m] = dpp_ror<1>(acc[ai][1][m][n][e]); L[m] = dpp_ror<15>(acc[ai][1][m][n][e]); }
; #pragma unroll
;                         for (int m = 0; m < 4; ++m) {
;                             const float up = (fr == 0) ? R[m > 0 ? m - 1 : 0] : R[m];
;                             const float dn = (fr == 15) ? L[m < 3 ? m + 1 : 3] : L[m];
;                             xv[m][eh] = up * w0[n][e] + acc[ai][1][m][n][e] * w1[n][e] + dn * w2[n][e] + bb[n][e];
;                         } }
; #pragma unroll
;                     for (int m = 0; m < 4; ++m) {
;                         const float p0 = __builtin_amdgcn_exp2f(fminf(-1.4426950408889634f * xv[m][0], 60.0f)) + 1.0f, p1 = __builtin_amdgcn_exp2f(fminf(-1.4426950408889634f * xv[m][1], 60.0f)) + 1.0f;
;                         const float r = __builtin_amdgcn_rcpf(p0 * p1);
;                         const bool edge = (m == 0 && fr == 0) || (m == 3 && fr == 15);
;                         ov[m][0] = edge ? acc[ai][0][m][n][2 * ep] : xv[m][0] * (r * p1) * acc[ai][0][m][n][2 * ep];
;                         ov[m][1] = edge ? acc[ai][0][m][n][2 * ep + 1] : xv[m][1] * (r * p0) * acc[ai][0][m][n][2 * ep + 1];
;                     }
; #pragma unroll
;                     for (int m = 0; m < 4; ++m) op[m][n][ep] = cvt_pk_bf16(ov[m][0], ov[m][1]);
	v_cndmask_b32_e64 v203, v203, v201, s[48:49]
	v_cndmask_b32_e64 v200, v200, v198, s[48:49]
	v_cndmask_b32_e64 v201, v201, v199, s[48:49]
	v_cndmask_b32_e64 v198, v198, v196, s[48:49]
	v_cndmask_b32_e64 v199, v199, v197, s[48:49]
	v_cndmask_b32_e64 v204, v204, v208, s[50:51]
	v_cndmask_b32_e64 v205, v205, v209, s[50:51]
	v_cndmask_b32_e64 v208, v208, v210, s[50:51]
	v_cndmask_b32_e64 v209, v209, v211, s[50:51]
	v_cndmask_b32_e64 v210, v210, v214, s[50:51]
	v_cndmask_b32_e64 v211, v211, v215, s[50:51]
	v_pk_fma_f32 v[204:205], v[204:205], v[136:137], v[132:133]
	v_pk_fma_f32 v[208:209], v[208:209], v[136:137], v[132:133]
	v_pk_fma_f32 v[210:211], v[210:211], v[136:137], v[132:133]
	v_pk_fma_f32 v[214:215], v[214:215], v[136:137], v[132:133]
	v_pk_fma_f32 v[204:205], v[14:15], v[128:129], v[204:205]
	v_pk_fma_f32 v[208:209], v[64:65], v[128:129], v[208:209]
	v_pk_fma_f32 v[210:211], v[60:61], v[128:129], v[210:211]
	v_pk_fma_f32 v[214:215], v[6:7], v[128:129], v[214:215]
	v_pk_fma_f32 v[204:205], v[196:197], v[124:125], v[204:205]
	v_pk_fma_f32 v[208:209], v[198:199], v[124:125], v[208:209]
	v_pk_fma_f32 v[210:211], v[200:201], v[124:125], v[210:211]
	v_pk_fma_f32 v[214:215], v[202:203], v[124:125], v[214:215]
	v_pk_mul_f32 v[196:197], v[204:205], s[52:53]
	v_pk_mul_f32 v[198:199], v[208:209], s[52:53]
	v_pk_mul_f32 v[200:201], v[210:211], s[52:53]
	v_pk_mul_f32 v[202:203], v[214:215], s[52:53]
	v_min_f32_e32 v196, 0x42700000, v196
	v_min_f32_e32 v197, 0x42700000, v197
	v_min_f32_e32 v198, 0x42700000, v198
	v_min_f32_e32 v199, 0x42700000, v199
	v_min_f32_e32 v200, 0x42700000, v200
	v_min_f32_e32 v201, 0x42700000, v201
	v_min_f32_e32 v202, 0x42700000, v202
	v_min_f32_e32 v203, 0x42700000, v203
	v_exp_f32_e32 v196, v196
	v_exp_f32_e32 v197, v197
	v_exp_f32_e32 v198, v198
	v_exp_f32_e32 v199, v199
	v_exp_f32_e32 v200, v200
	v_exp_f32_e32 v201, v201
	v_exp_f32_e32 v202, v202
	v_exp_f32_e32 v203, v203
	v_pk_add_f32 v[196:197], v[196:197], 1.0 op_sel_hi:[1,0]
	v_pk_add_f32 v[198:199], v[198:199], 1.0 op_sel_hi:[1,0]
	v_pk_add_f32 v[200:201], v[200:201], 1.0 op_sel_hi:[1,0]
	v_pk_add_f32 v[202:203], v[202:203], 1.0 op_sel_hi:[1,0]
	v_mul_f32_e32 v216, v196, v197
	v_mul_f32_e32 v217, v198, v199
	v_mul_f32_e32 v218, v200, v201
	v_mul_f32_e32 v219, v202, v203
	v_rcp_f32_e32 v216, v216
	v_rcp_f32_e32 v217, v217
	v_rcp_f32_e32 v218, v218
	v_rcp_f32_e32 v219, v219
	v_pk_mul_f32 v[196:197], v[196:197], v[216:217] op_sel:[1,0] op_sel_hi:[0,0]
	v_pk_mul_f32 v[198:199], v[198:199], v[216:217] op_sel:[1,1] op_sel_hi:[0,1]
	v_pk_mul_f32 v[200:201], v[200:201], v[218:219] op_sel:[1,0] op_sel_hi:[0,0]
	v_pk_mul_f32 v[202:203], v[202:203], v[218:219] op_sel:[1,1] op_sel_hi:[0,1]
	v_pk_mul_f32 v[204:205], v[204:205], v[196:197]
	v_pk_mul_f32 v[208:209], v[208:209], v[198:199]
	v_pk_mul_f32 v[210:211], v[210:211], v[200:201]
	v_pk_mul_f32 v[214:215], v[214:215], v[202:203]
	v_pk_mul_f32 v[204:205], v[204:205], v[56:57]
	v_pk_mul_f32 v[208:209], v[208:209], v[52:53]
	v_pk_mul_f32 v[210:211], v[210:211], v[48:49]
	v_pk_mul_f32 v[214:215], v[214:215], v[44:45]
	v_cndmask_b32_e64 v204, v204, v56, s[48:49]
	v_cndmask_b32_e64 v205, v205, v57, s[48:49]
	v_cndmask_b32_e64 v214, v214, v44, s[50:51]
	v_cndmask_b32_e64 v215, v215, v45, s[50:51]
	v_cvt_pk_bf16_f32 v55, v204, v205
	v_cvt_pk_bf16_f32 v51, v208, v209
	v_cvt_pk_bf16_f32 v47, v210, v211
	v_cvt_pk_bf16_f32 v43, v214, v215
	v_mov_b32_dpp v196, v8 row_ror:1 row_mask:0xf bank_mask:0xf
	v_mov_b32_dpp v197, v9 row_ror:1 row_mask:0xf bank_mask:0xf
	v_mov_b32_dpp v198, v38 row_ror:1 row_mask:0xf bank_mask:0xf
	v_mov_b32_dpp v199, v39 row_ror:1 row_mask:0xf bank_mask:0xf
	v_mov_b32_dpp v200, v34 row_ror:1 row_mask:0xf bank_mask:0xf
	v_mov_b32_dpp v201, v35 row_ror:1 row_mask:0xf bank_mask:0xf
	v_mov_b32_dpp v202, v0 row_ror:1 row_mask:0xf bank_mask:0xf
	v_mov_b32_dpp v203, v1 row_ror:1 row_mask:0xf bank_mask:0xf
	v_mov_b32_dpp v204, v8 row_ror:15 row_mask:0xf bank_mask:0xf
	v_mov_b32_dpp v205, v9 row_ror:15 row_mask:0xf bank_mask:0xf
	v_mov_b32_dpp v208, v38 row_ror:15 row_mask:0xf bank_mask:0xf
	v_mov_b32_dpp v209, v39 row_ror:15 row_mask:0xf bank_mask:0xf
	v_mov_b32_dpp v210, v34 row_ror:15 row_mask:0xf bank_mask:0xf
	v_mov_b32_dpp v211, v35 row_ror:15 row_mask:0xf bank_mask:0xf
	v_mov_b32_dpp v214, v0 row_ror:15 row_mask:0xf bank_mask:0xf
	v_mov_b32_dpp v215, v1 row_ror:15 row_mask:0xf bank_mask:0xf
	v_cndmask_b32_e64 v202, v202, v200, s[48:49]
	v_cndmask_b32_e64 v203, v203, v201, s[48:49]
	v_cndmask_b32_e64 v200, v200, v198, s[48:49]
	v_cndmask_b32_e64 v201, v201, v199, s[48:49]
	v_cndmask_b32_e64 v198, v198, v196, s[48:49]
	v_cndmask_b32_e64 v199, v199, v197, s[48:49]
	v_cndmask_b32_e64 v204, v204, v208, s[50:51]
	v_cndmask_b32_e64 v205, v205, v209, s[50:51]
	v_cndmask_b32_e64 v208, v208, v210, s[50:51]
	v_cndmask_b32_e64 v209, v209, v211, s[50:51]
	v_cndmask_b32_e64 v210, v210, v214, s[50:51]
	v_cndmask_b32_e64 v211, v211, v215, s[50:51]
	v_pk_fma_f32 v[204:205], v[204:205], v[78:79], v[70:71]
	v_pk_fma_f32 v[208:209], v[208:209], v[78:79], v[70:71]
	v_pk_fma_f32 v[210:211], v[210:211], v[78:79], v[70:71]
	v_pk_fma_f32 v[214:215], v[214:215], v[78:79], v[70:71]
	v_pk_fma_f32 v[204:205], v[8:9], v[74:75], v[204:205]
	v_pk_fma_f32 v[208:209], v[38:39], v[74:75], v[208:209]
	v_pk_fma_f32 v[210:211], v[34:35], v[74:75], v[210:211]
	v_pk_fma_f32 v[214:215], v[0:1], v[74:75], v[214:215]
	v_pk_fma_f32 v[204:205], v[196:197], v[66:67], v[204:205]
	v_pk_fma_f32 v[208:209], v[198:199], v[66:67], v[208:209]
	v_pk_fma_f32 v[210:211], v[200:201], v[66:67], v[210:211]
	v_pk_fma_f32 v[214:215], v[202:203], v[66:67], v[214:215]
; template <int N> __device__ __forceinline__ float dpp_ror(float v) { return __builtin_bit_cast(float, __builtin_amdgcn_update_dpp(0, __builtin_bit_cast(int, v), 0x120 + N, 0xf, 0xf, false)); }
; __device__ __forceinline__ unsigned cvt_pk_bf16(float lo, float hi) { unsigned r; asm volatile("v_cvt_pk_bf16_f32 %0, %1, %2" : "=v"(r) : "v"(lo), "v"(hi)); return r; }
;     __device__ __forceinline__ void run(const f32x4 (&acc)[2][2][4][2], const Unit& u, int wr, int wc, int fr, int fq, PG8_LAS unsigned char* lds, int buf) const {
;     ...
;                     for (int eh = 0; eh < 2; ++eh) { const int e = 2 * ep + eh;
;                         float R[4], L[4];
; #pragma unroll
;                         for (int m = 0; m < 4; ++m) { R[m] = dpp_ror<1>(acc[ai][1][m][n][e]); L[m] = dpp_ror<15>(acc[ai][1][m][n][e]); }
; #pragma unroll
;                         for (int m = 0; m < 4; ++m) {
;                             const float up = (fr == 0) ? R[m > 0 ? m - 1 : 0] : R[m];
;                             const float dn = (fr == 15) ? L[m < 3 ? m + 1 : 3] : L[m];
;                             xv[m][eh] = up * w0[n][e] + acc[ai][1][m][n][e] * w1[n][e] + dn * w2[n][e] + bb[n][e];
;                         } }
; #pragma unroll
;                     for (int m = 0; m < 4; ++m) {
;                         const float p0 = __builtin_amdgcn_exp2f(fminf(-1.4426950408889634f * xv[m][0], 60.0f)) + 1.0f, p1 = __builtin_amdgcn_exp2f(fminf(-1.4426950408889634f * xv[m][1], 60.0f)) + 1.0f;
;                         const float r = __builtin_amdgcn_rcpf(p0 * p1);
;                         const bool edge = (m == 0 && fr == 0) || (m == 3 && fr == 15);
;                         ov[m][0] = edge ? acc[ai][0][m][n][2 * ep] : xv[m][0] * (r * p1) * acc[ai][0][m][n][2 * ep];
;                         ov[m][1] = edge ? acc[ai][0][m][n][2 * ep + 1] : xv[m][1] * (r * p0) * acc[ai][0][m][n][2 * ep + 1];
;                     }
; #pragma unroll
;                     for (int m = 0; m < 4; ++m) op[m][n][ep] = cvt_pk_bf16(ov[m][0], ov[m][1]);
	v_pk_mul_f32 v[196:197], v[204:205], s[52:53]
	v_pk_mul_f32 v[198:199], v[208:209], s[52:53]
	v_pk_mul_f32 v[200:201], v[210:211], s[52:53]
	v_pk_mul_f32 v[202:203], v[214:215], s[52:53]
	v_min_f32_e32 v196, 0x42700000, v196
	v_min_f32_e32 v197, 0x42700000, v197
	v_min_f32_e32 v198, 0x42700000, v198
	v_min_f32_e32 v199, 0x42700000, v199
	v_min_f32_e32 v200, 0x42700000, v200
	v_min_f32_e32 v201, 0x42700000, v201
	v_min_f32_e32 v202, 0x42700000, v202
	v_min_f32_e32 v203, 0x42700000, v203
	v_exp_f32_e32 v196, v196
	v_exp_f32_e32 v197, v197
	v_exp_f32_e32 v198, v198
	v_exp_f32_e32 v199, v199
	v_exp_f32_e32 v200, v200
	v_exp_f32_e32 v201, v201
	v_exp_f32_e32 v202, v202
	v_exp_f32_e32 v203, v203
	v_pk_add_f32 v[196:197], v[196:197], 1.0 op_sel_hi:[1,0]
	v_pk_add_f32 v[198:199], v[198:199], 1.0 op_sel_hi:[1,0]
	v_pk_add_f32 v[200:201], v[200:201], 1.0 op_sel_hi:[1,0]
	v_pk_add_f32 v[202:203], v[202:203], 1.0 op_sel_hi:[1,0]
	v_mul_f32_e32 v216, v196, v197
	v_mul_f32_e32 v217, v198, v199
	v_mul_f32_e32 v218, v200, v201
	v_mul_f32_e32 v219, v202, v203
	v_rcp_f32_e32 v216, v216
	v_rcp_f32_e32 v217, v217
	v_rcp_f32_e32 v218, v218
	v_rcp_f32_e32 v219, v219
	v_pk_mul_f32 v[196:197], v[196:197], v[216:217] op_sel:[1,0] op_sel_hi:[0,0]
	v_pk_mul_f32 v[198:199], v[198:199], v[216:217] op_sel:[1,1] op_sel_hi:[0,1]
	v_pk_mul_f32 v[200:201], v[200:201], v[218:219] op_sel:[1,0] op_sel_hi:[0,0]
	v_pk_mul_f32 v[202:203], v[202:203], v[218:219] op_sel:[1,1] op_sel_hi:[0,1]
	v_pk_mul_f32 v[204:205], v[204:205], v[196:197]
	v_pk_mul_f32 v[208:209], v[208:209], v[198:199]
	v_pk_mul_f32 v[210:211], v[210:211], v[200:201]
	v_pk_mul_f32 v[214:215], v[214:215], v[202:203]
	v_pk_mul_f32 v[204:205], v[204:205], v[30:31]
	v_pk_mul_f32 v[208:209], v[208:209], v[26:27]
	v_pk_mul_f32 v[210:211], v[210:211], v[22:23]
	v_pk_mul_f32 v[214:215], v[214:215], v[16:17]
	v_cndmask_b32_e64 v204, v204, v30, s[48:49]
	v_cndmask_b32_e64 v205, v205, v31, s[48:49]
	v_cndmask_b32_e64 v214, v214, v16, s[50:51]
	v_cndmask_b32_e64 v215, v215, v17, s[50:51]
	v_cvt_pk_bf16_f32 v56, v204, v205
	v_cvt_pk_bf16_f32 v52, v208, v209
	v_cvt_pk_bf16_f32 v48, v210, v211
	v_cvt_pk_bf16_f32 v44, v214, v215
	v_mov_b32_dpp v196, v10 row_ror:1 row_mask:0xf bank_mask:0xf
	v_mov_b32_dpp v197, v11 row_ror:1 row_mask:0xf bank_mask:0xf
	v_mov_b32_dpp v198, v40 row_ror:1 row_mask:0xf bank_mask:0xf
	v_mov_b32_dpp v199, v41 row_ror:1 row_mask:0xf bank_mask:0xf
	v_mov_b32_dpp v200, v36 row_ror:1 row_mask:0xf bank_mask:0xf
	v_mov_b32_dpp v201, v37 row_ror:1 row_mask:0xf bank_mask:0xf
	v_mov_b32_dpp v202, v2 row_ror:1 row_mask:0xf bank_mask:0xf
	v_mov_b32_dpp v203, v3 row_ror:1 row_mask:0xf bank_mask:0xf
	v_mov_b32_dpp v204, v10 row_ror:15 row_mask:0xf bank_mask:0xf
	v_mov_b32_dpp v205, v11 row_ror:15 row_mask:0xf bank_mask:0xf
	v_mov_b32_dpp v208, v40 row_ror:15 row_mask:0xf bank_mask:0xf
	v_mov_b32_dpp v209, v41 row_ror:15 row_mask:0xf bank_mask:0xf
	v_mov_b32_dpp v210, v36 row_ror:15 row_mask:0xf bank_mask:0xf
	v_mov_b32_dpp v211, v37 row_ror:15 row_mask:0xf bank_mask:0xf
	v_mov_b32_dpp v214, v2 row_ror:15 row_mask:0xf bank_mask:0xf
	v_mov_b32_dpp v215, v3 row_ror:15 row_mask:0xf bank_mask:0xf
	v_cndmask_b32_e64 v202, v202, v200, s[48:49]
	v_cndmask_b32_e64 v203, v203, v201, s[48:49]
	v_cndmask_b32_e64 v200, v200, v198, s[48:49]
	v_cndmask_b32_e64 v201, v201, v199, s[48:49]
	v_cndmask_b32_e64 v198, v198, v196, s[48:49]
	v_cndmask_b32_e64 v199, v199, v197, s[48:49]
	v_cndmask_b32_e64 v204, v204, v208, s[50:51]
	v_cndmask_b32_e64 v205, v205, v209, s[50:51]
	v_cndmask_b32_e64 v208, v208, v210, s[50:51]
	v_cndmask_b32_e64 v209, v209, v211, s[50:51]
	v_cndmask_b32_e64 v210, v210, v214, s[50:51]
	v_cndmask_b32_e64 v211, v211, v215, s[50:51]
	v_pk_fma_f32 v[204:205], v[204:205], v[80:81], v[72:73]
	v_pk_fma_f32 v[208:209], v[208:209], v[80:81], v[72:73]
	v_pk_fma_f32 v[210:211], v[210:211], v[80:81], v[72:73]
	v_pk_fma_f32 v[214:215], v[214:215], v[80:81], v[72:73]
;     __device__ __forceinline__ void run(const f32x4 (&acc)[2][2][4][2], const Unit& u, int wr, int wc, int fr, int fq, PG8_LAS unsigned char* lds, int buf) const {
;     ...
;                     for (int eh = 0; eh < 2; ++eh) { const int e = 2 * ep + eh;
;                         float R[4], L[4];
; #pragma unroll
;                         for (int m = 0; m < 4; ++m) { R[m] = dpp_ror<1>(acc[ai][1][m][n][e]); L[m] = dpp_ror<15>(acc[ai][1][m][n][e]); }
; #pragma unroll
;                         for (int m = 0; m < 4; ++m) {
;                             const float up = (fr == 0) ? R[m > 0 ? m - 1 : 0] : R[m];
;                             const float dn = (fr == 15) ? L[m < 3 ? m + 1 : 3] : L[m];
;                             xv[m][eh] = up * w0[n][e] + acc[ai][1][m][n][e] * w1[n][e] + dn * w2[n][e] + bb[n][e];
;                         } }
; #pragma unroll
;                     for (int m = 0; m < 4; ++m) {
;                         const float p0 = __builtin_amdgcn_exp2f(fminf(-1.4426950408889634f * xv[m][0], 60.0f)) + 1.0f, p1 = __builtin_amdgcn_exp2f(fminf(-1.4426950408889634f * xv[m][1], 60.0f)) + 1.0f;
;                         const float r = __builtin_amdgcn_rcpf(p0 * p1);
;                         const bool edge = (m == 0 && fr == 0) || (m == 3 && fr == 15);
;                         ov[m][0] = edge ? acc[ai][0][m][n][2 * ep] : xv[m][0] * (r * p1) * acc[ai][0][m][n][2 * ep];
;                         ov[m][1] = edge ? acc[ai][0][m][n][2 * ep + 1] : xv[m][1] * (r * p0) * acc[ai][0][m][n][2 * ep + 1];
;                     }
; #pragma unroll
;                     for (int m = 0; m < 4; ++m) op[m][n][ep] = cvt_pk_bf16(ov[m][0], ov[m][1]);
;                     __builtin_amdgcn_sched_barrier(0);
;                 }
; #pragma unroll
;             for (int m = 0; m < 4; ++m) {
;                 u32x4 w; w.x = op[m][0][0]; w.y = op[m][0][1]; w.z = op[m][1][0]; w.w = op[m][1][1];
;                 *(u32x4*)(ACT + (size_t)(row0 + ai * HALF + m * 16) * 5632 + ch0) = w;
;             }
;             const int grp = u.pm * 4 + ai * 2 + wr;
;             if (fr <= 1) { const f32x4 g0 = acc[ai][1][0][0], g1 = acc[ai][1][0][1];
;                 u32x4 w; w.x = cvt_pk_bf16(g0[0], g0[1]); w.y = cvt_pk_bf16(g0[2], g0[3]); w.z = cvt_pk_bf16(g1[0], g1[1]); w.w = cvt_pk_bf16(g1[2], g1[3]);
;                 *(u32x4*)(GB + ((size_t)(grp * 4 + fr)) * 5632 + ch0) = w; }
	v_pk_fma_f32 v[204:205], v[10:11], v[76:77], v[204:205]
	v_pk_fma_f32 v[208:209], v[40:41], v[76:77], v[208:209]
	v_pk_fma_f32 v[210:211], v[36:37], v[76:77], v[210:211]
	v_pk_fma_f32 v[214:215], v[2:3], v[76:77], v[214:215]
	v_pk_fma_f32 v[204:205], v[196:197], v[68:69], v[204:205]
	v_pk_fma_f32 v[208:209], v[198:199], v[68:69], v[208:209]
	v_pk_fma_f32 v[210:211], v[200:201], v[68:69], v[210:211]
	v_pk_fma_f32 v[214:215], v[202:203], v[68:69], v[214:215]
	v_pk_mul_f32 v[196:197], v[204:205], s[52:53]
	v_pk_mul_f32 v[198:199], v[208:209], s[52:53]
	v_pk_mul_f32 v[200:201], v[210:211], s[52:53]
	v_pk_mul_f32 v[202:203], v[214:215], s[52:53]
	v_min_f32_e32 v196, 0x42700000, v196
	v_min_f32_e32 v197, 0x42700000, v197
	v_min_f32_e32 v198, 0x42700000, v198
	v_min_f32_e32 v199, 0x42700000, v199
	v_min_f32_e32 v200, 0x42700000, v200
	v_min_f32_e32 v201, 0x42700000, v201
	v_min_f32_e32 v202, 0x42700000, v202
	v_min_f32_e32 v203, 0x42700000, v203
	v_exp_f32_e32 v196, v196
	v_exp_f32_e32 v197, v197
	v_exp_f32_e32 v198, v198
	v_exp_f32_e32 v199, v199
	v_exp_f32_e32 v200, v200
	v_exp_f32_e32 v201, v201
	v_exp_f32_e32 v202, v202
	v_exp_f32_e32 v203, v203
	v_pk_add_f32 v[196:197], v[196:197], 1.0 op_sel_hi:[1,0]
	v_pk_add_f32 v[198:199], v[198:199], 1.0 op_sel_hi:[1,0]
	v_pk_add_f32 v[200:201], v[200:201], 1.0 op_sel_hi:[1,0]
	v_pk_add_f32 v[202:203], v[202:203], 1.0 op_sel_hi:[1,0]
	v_mul_f32_e32 v216, v196, v197
	v_mul_f32_e32 v217, v198, v199
	v_mul_f32_e32 v218, v200, v201
	v_mul_f32_e32 v219, v202, v203
	v_rcp_f32_e32 v216, v216
	v_rcp_f32_e32 v217, v217
	v_rcp_f32_e32 v218, v218
	v_rcp_f32_e32 v219, v219
	v_pk_mul_f32 v[196:197], v[196:197], v[216:217] op_sel:[1,0] op_sel_hi:[0,0]
	v_pk_mul_f32 v[198:199], v[198:199], v[216:217] op_sel:[1,1] op_sel_hi:[0,1]
	v_pk_mul_f32 v[200:201], v[200:201], v[218:219] op_sel:[1,0] op_sel_hi:[0,0]
	v_pk_mul_f32 v[202:203], v[202:203], v[218:219] op_sel:[1,1] op_sel_hi:[0,1]
	v_pk_mul_f32 v[204:205], v[204:205], v[196:197]
	v_pk_mul_f32 v[208:209], v[208:209], v[198:199]
	v_pk_mul_f32 v[210:211], v[210:211], v[200:201]
	v_pk_mul_f32 v[214:215], v[214:215], v[202:203]
	v_pk_mul_f32 v[204:205], v[204:205], v[32:33]
	v_pk_mul_f32 v[208:209], v[208:209], v[28:29]
	v_pk_mul_f32 v[210:211], v[210:211], v[24:25]
	v_pk_mul_f32 v[214:215], v[214:215], v[18:19]
	v_cndmask_b32_e64 v204, v204, v32, s[48:49]
	v_cndmask_b32_e64 v205, v205, v33, s[48:49]
	v_cndmask_b32_e64 v214, v214, v18, s[50:51]
	v_cndmask_b32_e64 v215, v215, v19, s[50:51]
	v_cvt_pk_bf16_f32 v57, v204, v205
	v_cvt_pk_bf16_f32 v53, v208, v209
	v_cvt_pk_bf16_f32 v49, v210, v211
	v_cvt_pk_bf16_f32 v45, v214, v215
	s_movk_i32 s64, 0x2c00
	v_add_u32_e32 v18, 0x80, v194
	v_mov_b64_e32 v[16:17], s[26:27]
	v_mad_i64_i32 v[18:19], s[48:49], v18, s64, v[16:17]
	v_lshl_add_u64 v[18:19], v[18:19], 0, v[100:101]
	global_store_dwordx4 v[18:19], v[54:57], off
	v_add_u32_e32 v18, 0x90, v194
	v_mad_i64_i32 v[18:19], s[48:49], v18, s64, v[16:17]
	v_lshl_add_u64 v[18:19], v[18:19], 0, v[100:101]
	global_store_dwordx4 v[18:19], v[50:53], off
	v_add_u32_e32 v18, 0xa0, v194
	v_mad_i64_i32 v[18:19], s[48:49], v18, s64, v[16:17]
	v_lshl_add_u64 v[18:19], v[18:19], 0, v[100:101]
	global_store_dwordx4 v[18:19], v[46:49], off
	v_add_u32_e32 v18, 0xb0, v194
	v_mad_i64_i32 v[16:17], s[48:49], v18, s64, v[16:17]
	v_lshl_add_u64 v[16:17], v[16:17], 0, v[100:101]
	s_add_i32 s23, s23, 2
	global_store_dwordx4 v[16:17], v[42:45], off
	s_and_saveexec_b64 s[48:49], s[38:39]
	s_cbranch_execz .LBB0_1169
	v_cvt_pk_bf16_f32 v12, v12, v13
	v_cvt_pk_bf16_f32 v13, v14, v15
	v_cvt_pk_bf16_f32 v14, v8, v9
	v_cvt_pk_bf16_f32 v15, v10, v11
	v_lshl_or_b32 v10, s23, 2, v21
	v_mov_b64_e32 v[8:9], s[36:37]
	v_mad_i64_i32 v[8:9], s[50:51], v10, s64, v[8:9]
	v_lshl_add_u64 v[8:9], v[188:189], 1, v[8:9]
	global_store_dwordx4 v[8:9], v[12:15], off
	s_or_b64 exec, exec, s[48:49]
	s_and_saveexec_b64 s[48:49], s[40:41]
	s_cbranch_execnz .LBB0_1170
